# loop grid barriers count arrivals on an own monotonic device-memory counter instead of the runtime barrier struct
# speedup vs baseline: 1.0667x; 1.0019x over previous
; __global__ void __launch_bounds__(256, 2) mega(P p, int ph_lo, int ph_hi) {
;     ...
;       grid.sync();
.LBB0_1058:
	buffer_wbl2 sc1
	v_readlane_b32 s8, v253, 5
	v_readlane_b32 s4, v254, 12
	v_readlane_b32 s5, v254, 13
	v_mov_b32_e32 v248, 0x588200
	v_mov_b32_e32 v2, 1
	s_add_u32 s5, s5, s4
	s_mul_i32 s9, s5, s8
	s_add_u32 s9, s9, -1
	s_waitcnt vmcnt(0)
	global_atomic_add v2, v248, v2, s[58:59] sc0
	s_waitcnt vmcnt(0)
	v_cmp_eq_u32_e32 vcc, s9, v2
	s_and_saveexec_b64 s[4:5], vcc
	s_cbranch_execz .LBB0_1063
	v_mov_b32_e32 v248, 0x588400
	v_mov_b32_e32 v249, 1
	global_atomic_add v248, v249, s[58:59]
	v_add_u32_e32 v248, 0x1000, v248
	global_atomic_add v248, v249, s[58:59]
	v_add_u32_e32 v248, 0x1000, v248
	global_atomic_add v248, v249, s[58:59]
	v_add_u32_e32 v248, 0x1000, v248
	global_atomic_add v248, v249, s[58:59]
	v_add_u32_e32 v248, 0x1000, v248
	global_atomic_add v248, v249, s[58:59]
	v_add_u32_e32 v248, 0x1000, v248
	global_atomic_add v248, v249, s[58:59]
	v_add_u32_e32 v248, 0x1000, v248
	global_atomic_add v248, v249, s[58:59]
	v_add_u32_e32 v248, 0x1000, v248
	global_atomic_add v248, v249, s[58:59]
	v_add_u32_e32 v248, 0x1000, v248
